# LRU pass 2: look-back loads of both directions issued together (one exposed latency per tile)
# baseline (speedup 1.0000x reference)
; __device__ __forceinline__ float bf2f(u16 h) { return __uint_as_float(((unsigned)h) << 16); }
; __device__ __forceinline__ void lru_tile(const Params& P, int chunk, int head, int pass, char* smem_raw) {
;     ...
;     const int r = row0 + q * 32;
;     float uv[35];
; #pragma unroll
;     for (int i = 0; i < 35; ++i) {
;       const int rr = r - 2 + i;
;       uv[i] = (rr >= seq_lo && rr < seq_hi) ? bf2f(zu[(long)rr * 1536]) : 0.f;
;     }
;     __syncthreads();
; #pragma unroll
;     for (int i = 0; i < 32; ++i) {
;       const float v = cb + uv[i] * w0 + uv[i + 1] * w1 + uv[i + 2] * w2 + uv[i + 3] * w3;
;       sm_uc[(q * 32 + i) * LDSS + ch] = f2bf(v);
.Lmy_lrub_fl:
	s_cmp_eq_u32 s57, 0
	s_cselect_b64 s[0:1], s[84:85], 0
	s_cmp_eq_u32 s57, s60
	s_cselect_b64 s[4:5], s[86:87], 0
	v_cndmask_b32_e64 v202, 1.0, 0, s[0:1]
	v_cndmask_b32_e64 v203, 1.0, 0, s[4:5]
	s_barrier
	s_waitcnt vmcnt(32)
	v_lshlrev_b32_e32 v90, 16, v32
	v_lshlrev_b32_e32 v91, 16, v33
	v_lshlrev_b32_e32 v92, 16, v34
	v_lshlrev_b32_e32 v93, 16, v35
	v_lshlrev_b32_e32 v94, 16, v36
	v_lshlrev_b32_e32 v95, 16, v37
	v_lshlrev_b32_e32 v96, 16, v38
	v_lshlrev_b32_e32 v97, 16, v39
	v_lshlrev_b32_e32 v98, 16, v40
	v_lshlrev_b32_e32 v99, 16, v41
	v_lshlrev_b32_e32 v100, 16, v42
	v_lshlrev_b32_e32 v101, 16, v43
	v_lshlrev_b32_e32 v102, 16, v44
	v_lshlrev_b32_e32 v103, 16, v45
	v_lshlrev_b32_e32 v104, 16, v46
	v_lshlrev_b32_e32 v105, 16, v47
	v_lshlrev_b32_e32 v106, 16, v48
	v_lshlrev_b32_e32 v107, 16, v49
	v_lshlrev_b32_e32 v108, 16, v50
	v_lshlrev_b32_e32 v109, 16, v51
	v_lshlrev_b32_e32 v110, 16, v52
	v_lshlrev_b32_e32 v111, 16, v53
	v_lshlrev_b32_e32 v112, 16, v54
	v_lshlrev_b32_e32 v113, 16, v55
	v_lshlrev_b32_e32 v114, 16, v56
	v_lshlrev_b32_e32 v115, 16, v57
	v_lshlrev_b32_e32 v116, 16, v58
	v_lshlrev_b32_e32 v117, 16, v59
	v_lshlrev_b32_e32 v118, 16, v60
	v_lshlrev_b32_e32 v119, 16, v61
	v_lshlrev_b32_e32 v120, 16, v62
	v_lshlrev_b32_e32 v121, 16, v63
	v_lshlrev_b32_e32 v122, 16, v64
	v_lshlrev_b32_e32 v123, 16, v66
	v_lshlrev_b32_e32 v124, 16, v69
	v_mul_f32_e32 v90, v90, v202
	v_mul_f32_e32 v91, v91, v202
	v_mul_f32_e32 v124, v124, v203
	v_fma_f32 v162, v90, v65, v73
	v_fma_f32 v162, v91, v67, v162
	v_fma_f32 v162, v92, v68, v162
	v_fma_f32 v162, v93, v70, v162
	v_fma_f32 v163, v91, v65, v73
	v_fma_f32 v163, v92, v67, v163
	v_fma_f32 v163, v93, v68, v163
	v_fma_f32 v163, v94, v70, v163
	v_fma_f32 v164, v92, v65, v73
	v_fma_f32 v164, v93, v67, v164
	v_fma_f32 v164, v94, v68, v164
	v_fma_f32 v164, v95, v70, v164
	v_fma_f32 v165, v93, v65, v73
	v_fma_f32 v165, v94, v67, v165
	v_fma_f32 v165, v95, v68, v165
	v_fma_f32 v165, v96, v70, v165
	v_fma_f32 v166, v94, v65, v73
	v_fma_f32 v166, v95, v67, v166
	v_fma_f32 v166, v96, v68, v166
	v_fma_f32 v166, v97, v70, v166
	v_fma_f32 v167, v95, v65, v73
	v_fma_f32 v167, v96, v67, v167
	v_fma_f32 v167, v97, v68, v167
	v_fma_f32 v167, v98, v70, v167
	v_fma_f32 v168, v96, v65, v73
	v_fma_f32 v168, v97, v67, v168
	v_fma_f32 v168, v98, v68, v168
	v_fma_f32 v168, v99, v70, v168
	v_fma_f32 v169, v97, v65, v73
	v_fma_f32 v169, v98, v67, v169
	v_fma_f32 v169, v99, v68, v169
	v_fma_f32 v169, v100, v70, v169
	v_fma_f32 v170, v98, v65, v73
	v_fma_f32 v170, v99, v67, v170
	v_fma_f32 v170, v100, v68, v170
	v_fma_f32 v170, v101, v70, v170
	v_fma_f32 v171, v99, v65, v73
	v_fma_f32 v171, v100, v67, v171
	v_fma_f32 v171, v101, v68, v171
	v_fma_f32 v171, v102, v70, v171
	v_fma_f32 v172, v100, v65, v73
	v_fma_f32 v172, v101, v67, v172
	v_fma_f32 v172, v102, v68, v172
	v_fma_f32 v172, v103, v70, v172
	v_fma_f32 v173, v101, v65, v73
	v_fma_f32 v173, v102, v67, v173
	v_fma_f32 v173, v103, v68, v173
	v_fma_f32 v173, v104, v70, v173
	v_fma_f32 v174, v102, v65, v73
	v_fma_f32 v174, v103, v67, v174
	v_fma_f32 v174, v104, v68, v174
	v_fma_f32 v174, v105, v70, v174
	v_fma_f32 v175, v103, v65, v73
	v_fma_f32 v175, v104, v67, v175
	v_fma_f32 v175, v105, v68, v175
	v_fma_f32 v175, v106, v70, v175
	v_fma_f32 v176, v104, v65, v73
	v_fma_f32 v176, v105, v67, v176
	v_fma_f32 v176, v106, v68, v176
	v_fma_f32 v176, v107, v70, v176
	v_fma_f32 v177, v105, v65, v73
	v_fma_f32 v177, v106, v67, v177
	v_fma_f32 v177, v107, v68, v177
	v_fma_f32 v177, v108, v70, v177
	v_fma_f32 v178, v106, v65, v73
	v_fma_f32 v178, v107, v67, v178
	v_fma_f32 v178, v108, v68, v178
	v_fma_f32 v178, v109, v70, v178
	v_fma_f32 v179, v107, v65, v73
	v_fma_f32 v179, v108, v67, v179
	v_fma_f32 v179, v109, v68, v179
	v_fma_f32 v179, v110, v70, v179
	v_fma_f32 v180, v108, v65, v73
	v_fma_f32 v180, v109, v67, v180
	v_fma_f32 v180, v110, v68, v180
	v_fma_f32 v180, v111, v70, v180
	v_fma_f32 v181, v109, v65, v73
	v_fma_f32 v181, v110, v67, v181
	v_fma_f32 v181, v111, v68, v181
	v_fma_f32 v181, v112, v70, v181
	v_fma_f32 v182, v110, v65, v73
	v_fma_f32 v182, v111, v67, v182
	v_fma_f32 v182, v112, v68, v182
	v_fma_f32 v182, v113, v70, v182
	v_fma_f32 v183, v111, v65, v73
	v_fma_f32 v183, v112, v67, v183
	v_fma_f32 v183, v113, v68, v183
	v_fma_f32 v183, v114, v70, v183
	v_fma_f32 v184, v112, v65, v73
	v_fma_f32 v184, v113, v67, v184
	v_fma_f32 v184, v114, v68, v184
	v_fma_f32 v184, v115, v70, v184
	v_fma_f32 v185, v113, v65, v73
	v_fma_f32 v185, v114, v67, v185
	v_fma_f32 v185, v115, v68, v185
	v_fma_f32 v185, v116, v70, v185
	v_fma_f32 v186, v114, v65, v73
	v_fma_f32 v186, v115, v67, v186
	v_fma_f32 v186, v116, v68, v186
	v_fma_f32 v186, v117, v70, v186
	v_fma_f32 v187, v115, v65, v73
	v_fma_f32 v187, v116, v67, v187
	v_fma_f32 v187, v117, v68, v187
	v_fma_f32 v187, v118, v70, v187
	v_fma_f32 v188, v116, v65, v73
	v_fma_f32 v188, v117, v67, v188
	v_fma_f32 v188, v118, v68, v188
	v_fma_f32 v188, v119, v70, v188
	v_fma_f32 v189, v117, v65, v73
	v_fma_f32 v189, v118, v67, v189
	v_fma_f32 v189, v119, v68, v189
	v_fma_f32 v189, v120, v70, v189
	v_fma_f32 v190, v118, v65, v73
	v_fma_f32 v190, v119, v67, v190
	v_fma_f32 v190, v120, v68, v190
	v_fma_f32 v190, v121, v70, v190
	v_fma_f32 v191, v119, v65, v73
	v_fma_f32 v191, v120, v67, v191
	v_fma_f32 v191, v121, v68, v191
	v_fma_f32 v191, v122, v70, v191
	v_fma_f32 v192, v120, v65, v73
	v_fma_f32 v192, v121, v67, v192
	v_fma_f32 v192, v122, v68, v192
	v_fma_f32 v192, v123, v70, v192
	v_fma_f32 v193, v121, v65, v73
	v_fma_f32 v193, v122, v67, v193
	v_fma_f32 v193, v123, v68, v193
	v_fma_f32 v193, v124, v70, v193
; __device__ __forceinline__ void lru_tile(const Params& P, int chunk, int head, int pass, char* smem_raw) {
;     ...
;     for (int i = 0; i < 32; ++i) {
;       const float v = cb + uv[i] * w0 + uv[i + 1] * w1 + uv[i + 2] * w2 + uv[i + 3] * w3;
;       sm_uc[(q * 32 + i) * LDSS + ch] = f2bf(v);
;     }
;   }
;   if (pass == 2 && tid < 128) {
;     const int d = tid >> 6;
;     float h = 0.f;
;     const float2* S = P.summ + (long)d * 264 * 512 + gch;
;     if (chunk < 256) {
;       const int b = chunk >> 6, j = chunk & 63;
;       if (d == 0) {
;         float2 s = S[(long)(256 + 2 * b) * 512]; h = s.x * h + s.y;
;         s = S[(long)(256 + 2 * b + 1) * 512]; h = s.x * h + s.y;
;         int i = 0;
;         for (; i + 8 <= j; i += 8) {
;           float2 sv[8];
; #pragma unroll
;           for (int u = 0; u < 8; ++u) sv[u] = S[(long)(b * 64 + i + u) * 512];
; #pragma unroll
;           for (int u = 0; u < 8; ++u) h = sv[u].x * h + sv[u].y;
;         }
;         for (; i < j; ++i) { s = S[(long)(b * 64 + i) * 512]; h = s.x * h + s.y; }
	v_cvt_pk_bf16_f32 v162, v162, v162
	v_cvt_pk_bf16_f32 v163, v163, v163
	v_cvt_pk_bf16_f32 v164, v164, v164
	v_cvt_pk_bf16_f32 v165, v165, v165
	v_cvt_pk_bf16_f32 v166, v166, v166
	v_cvt_pk_bf16_f32 v167, v167, v167
	v_cvt_pk_bf16_f32 v168, v168, v168
	v_cvt_pk_bf16_f32 v169, v169, v169
	v_cvt_pk_bf16_f32 v170, v170, v170
	v_cvt_pk_bf16_f32 v171, v171, v171
	v_cvt_pk_bf16_f32 v172, v172, v172
	v_cvt_pk_bf16_f32 v173, v173, v173
	v_cvt_pk_bf16_f32 v174, v174, v174
	v_cvt_pk_bf16_f32 v175, v175, v175
	v_cvt_pk_bf16_f32 v176, v176, v176
	v_cvt_pk_bf16_f32 v177, v177, v177
	v_cvt_pk_bf16_f32 v178, v178, v178
	v_cvt_pk_bf16_f32 v179, v179, v179
	v_cvt_pk_bf16_f32 v180, v180, v180
	v_cvt_pk_bf16_f32 v181, v181, v181
	v_cvt_pk_bf16_f32 v182, v182, v182
	v_cvt_pk_bf16_f32 v183, v183, v183
	v_cvt_pk_bf16_f32 v184, v184, v184
	v_cvt_pk_bf16_f32 v185, v185, v185
	v_cvt_pk_bf16_f32 v186, v186, v186
	v_cvt_pk_bf16_f32 v187, v187, v187
	v_cvt_pk_bf16_f32 v188, v188, v188
	v_cvt_pk_bf16_f32 v189, v189, v189
	v_cvt_pk_bf16_f32 v190, v190, v190
	v_cvt_pk_bf16_f32 v191, v191, v191
	v_cvt_pk_bf16_f32 v192, v192, v192
	v_cvt_pk_bf16_f32 v193, v193, v193
	ds_write_b16 v89, v162 offset:0
	ds_write_b16 v89, v163 offset:128
	ds_write_b16 v130, v164 offset:256
	ds_write_b16 v130, v165 offset:384
	ds_write_b16 v89, v166 offset:512
	ds_write_b16 v89, v167 offset:640
	ds_write_b16 v130, v168 offset:768
	ds_write_b16 v130, v169 offset:896
	ds_write_b16 v89, v170 offset:1024
	ds_write_b16 v89, v171 offset:1152
	ds_write_b16 v130, v172 offset:1280
	ds_write_b16 v130, v173 offset:1408
	ds_write_b16 v89, v174 offset:1536
	ds_write_b16 v89, v175 offset:1664
	ds_write_b16 v130, v176 offset:1792
	ds_write_b16 v130, v177 offset:1920
	ds_write_b16 v89, v178 offset:2048
	ds_write_b16 v89, v179 offset:2176
	ds_write_b16 v130, v180 offset:2304
	ds_write_b16 v130, v181 offset:2432
	ds_write_b16 v89, v182 offset:2560
	ds_write_b16 v89, v183 offset:2688
	ds_write_b16 v130, v184 offset:2816
	ds_write_b16 v130, v185 offset:2944
	ds_write_b16 v89, v186 offset:3072
	ds_write_b16 v89, v187 offset:3200
	ds_write_b16 v130, v188 offset:3328
	ds_write_b16 v130, v189 offset:3456
	ds_write_b16 v89, v190 offset:3584
	ds_write_b16 v89, v191 offset:3712
	ds_write_b16 v130, v192 offset:3840
	ds_write_b16 v130, v193 offset:3968
	v_lshlrev_b32_e32 v162, 16, v162
	v_lshlrev_b32_e32 v163, 16, v163
	v_lshlrev_b32_e32 v164, 16, v164
	v_lshlrev_b32_e32 v165, 16, v165
	v_lshlrev_b32_e32 v166, 16, v166
	v_lshlrev_b32_e32 v167, 16, v167
	v_lshlrev_b32_e32 v168, 16, v168
	v_lshlrev_b32_e32 v169, 16, v169
	v_lshlrev_b32_e32 v170, 16, v170
	v_lshlrev_b32_e32 v171, 16, v171
	v_lshlrev_b32_e32 v172, 16, v172
	v_lshlrev_b32_e32 v173, 16, v173
	v_lshlrev_b32_e32 v174, 16, v174
	v_lshlrev_b32_e32 v175, 16, v175
	v_lshlrev_b32_e32 v176, 16, v176
	v_lshlrev_b32_e32 v177, 16, v177
	v_lshlrev_b32_e32 v178, 16, v178
	v_lshlrev_b32_e32 v179, 16, v179
	v_lshlrev_b32_e32 v180, 16, v180
	v_lshlrev_b32_e32 v181, 16, v181
	v_lshlrev_b32_e32 v182, 16, v182
	v_lshlrev_b32_e32 v183, 16, v183
	v_lshlrev_b32_e32 v184, 16, v184
	v_lshlrev_b32_e32 v185, 16, v185
	v_lshlrev_b32_e32 v186, 16, v186
	v_lshlrev_b32_e32 v187, 16, v187
	v_lshlrev_b32_e32 v188, 16, v188
	v_lshlrev_b32_e32 v189, 16, v189
	v_lshlrev_b32_e32 v190, 16, v190
	v_lshlrev_b32_e32 v191, 16, v191
	v_lshlrev_b32_e32 v192, 16, v192
	v_lshlrev_b32_e32 v193, 16, v193
	s_waitcnt lgkmcnt(0)
	s_barrier
	v_mov_b32_e32 v148, 0
	v_mov_b32_e32 v149, 0
	s_cmp_lt_u32 s71, 256
	s_cbranch_scc0 .Lmy_lrub_lbctx
	s_lshl_b32 s0, s56, 3
	s_add_u32 s0, s0, 0x0
	s_add_u32 s4, s18, s0
	s_addc_u32 s5, s19, 0
	s_lshr_b32 s0, s71, 6
	s_lshl_b32 s1, s0, 1
	s_add_u32 s1, s1, 256
	s_add_u32 s60, s1, 0
	s_lshl_b32 s60, s60, 12
	s_add_u32 s60, s4, s60
	s_addc_u32 s61, s5, 0
	global_load_dwordx2 v[0:1], v250, s[60:61]
	s_add_u32 s60, s1, 1
	s_lshl_b32 s60, s60, 12
	s_add_u32 s60, s4, s60
	s_addc_u32 s61, s5, 0
	global_load_dwordx2 v[2:3], v250, s[60:61]
	s_lshl_b32 s0, s0, 6
	v_bfe_u32 v150, v152, 4, 2
	s_mov_b32 s1, s57
	v_lshl_add_u32 v136, v150, 16, v250
	s_lshl_b32 s60, s0, 12
	v_lshlrev_b32_e32 v150, 4, v150
	v_sub_u32_e32 v150, s1, v150
	s_add_u32 s60, s4, s60
	s_addc_u32 s61, s5, 0
	global_load_dwordx2 v[4:5], v136, s[60:61]
	s_add_u32 s60, s60, 0x1000
	s_addc_u32 s61, s61, 0
	global_load_dwordx2 v[6:7], v136, s[60:61]
	s_add_u32 s60, s60, 0x1000
	s_addc_u32 s61, s61, 0
	global_load_dwordx2 v[8:9], v136, s[60:61]
	s_add_u32 s60, s60, 0x1000
	s_addc_u32 s61, s61, 0
	global_load_dwordx2 v[10:11], v136, s[60:61]
	s_add_u32 s60, s60, 0x1000
	s_addc_u32 s61, s61, 0
	global_load_dwordx2 v[12:13], v136, s[60:61]
	s_add_u32 s60, s60, 0x1000
	s_addc_u32 s61, s61, 0
	global_load_dwordx2 v[14:15], v136, s[60:61]
	s_add_u32 s60, s60, 0x1000
	s_addc_u32 s61, s61, 0
	global_load_dwordx2 v[16:17], v136, s[60:61]
	s_add_u32 s60, s60, 0x1000
	s_addc_u32 s61, s61, 0
	global_load_dwordx2 v[18:19], v136, s[60:61]
	s_add_u32 s60, s60, 0x1000
	s_addc_u32 s61, s61, 0
	global_load_dwordx2 v[20:21], v136, s[60:61]
	s_add_u32 s60, s60, 0x1000
	s_addc_u32 s61, s61, 0
	global_load_dwordx2 v[22:23], v136, s[60:61]
	s_add_u32 s60, s60, 0x1000
	s_addc_u32 s61, s61, 0
	global_load_dwordx2 v[24:25], v136, s[60:61]
	s_add_u32 s60, s60, 0x1000
	s_addc_u32 s61, s61, 0
	global_load_dwordx2 v[26:27], v136, s[60:61]
	s_add_u32 s60, s60, 0x1000
	s_addc_u32 s61, s61, 0
	global_load_dwordx2 v[28:29], v136, s[60:61]
	s_add_u32 s60, s60, 0x1000
	s_addc_u32 s61, s61, 0
	global_load_dwordx2 v[30:31], v136, s[60:61]
	s_add_u32 s60, s60, 0x1000
	s_addc_u32 s61, s61, 0
	global_load_dwordx2 v[32:33], v136, s[60:61]
	s_add_u32 s60, s60, 0x1000
; __device__ __forceinline__ void lru_tile(const Params& P, int chunk, int head, int pass, char* smem_raw) {
;     ...
;     const float2* S = P.summ + (long)d * 264 * 512 + gch;
;     if (chunk < 256) {
;       const int b = chunk >> 6, j = chunk & 63;
;       if (d == 0) {
;         float2 s = S[(long)(256 + 2 * b) * 512]; h = s.x * h + s.y;
;         s = S[(long)(256 + 2 * b + 1) * 512]; h = s.x * h + s.y;
;         int i = 0;
;         for (; i + 8 <= j; i += 8) {
;           float2 sv[8];
; #pragma unroll
;           for (int u = 0; u < 8; ++u) sv[u] = S[(long)(b * 64 + i + u) * 512];
; #pragma unroll
;           for (int u = 0; u < 8; ++u) h = sv[u].x * h + sv[u].y;
;         }
;         for (; i < j; ++i) { s = S[(long)(b * 64 + i) * 512]; h = s.x * h + s.y; }
;       } else {
;         float2 s = S[(long)(256 + 2 * b + 1) * 512]; h = s.x * h + s.y;
;         s = S[(long)(256 + 2 * b) * 512]; h = s.x * h + s.y;
;         int i = 63;
;         for (; i - 8 >= j; i -= 8) {
;           float2 sv[8];
; #pragma unroll
;           for (int u = 0; u < 8; ++u) sv[u] = S[(long)(b * 64 + i - u) * 512];
; #pragma unroll
;           for (int u = 0; u < 8; ++u) h = sv[u].x * h + sv[u].y;
;         }
;         for (; i > j; --i) { s = S[(long)(b * 64 + i) * 512]; h = s.x * h + s.y; }
;       }
	s_addc_u32 s61, s61, 0
	global_load_dwordx2 v[34:35], v136, s[60:61]
	s_lshl_b32 s0, s56, 3
	s_add_u32 s0, s0, 0x108000
	s_add_u32 s4, s18, s0
	s_addc_u32 s5, s19, 0
	s_lshr_b32 s0, s71, 6
	s_lshl_b32 s1, s0, 1
	s_add_u32 s1, s1, 256
	s_add_u32 s60, s1, 1
	s_lshl_b32 s60, s60, 12
	s_add_u32 s60, s4, s60
	s_addc_u32 s61, s5, 0
	global_load_dwordx2 v[90:91], v250, s[60:61]
	s_add_u32 s60, s1, 0
	s_lshl_b32 s60, s60, 12
	s_add_u32 s60, s4, s60
	s_addc_u32 s61, s5, 0
	global_load_dwordx2 v[92:93], v250, s[60:61]
	s_lshl_b32 s0, s0, 6
	v_bfe_u32 v202, v152, 4, 2
	s_sub_u32 s1, 63, s57
	v_sub_u32_e32 v151, 3, v202
	v_lshl_add_u32 v151, v151, 16, v250
	s_add_u32 s60, s0, 15
	s_lshl_b32 s60, s60, 12
	v_lshlrev_b32_e32 v202, 4, v202
	v_sub_u32_e32 v202, s1, v202
	s_add_u32 s60, s4, s60
	s_addc_u32 s61, s5, 0
	global_load_dwordx2 v[94:95], v151, s[60:61]
	s_sub_u32 s60, s60, 0x1000
	s_subb_u32 s61, s61, 0
	global_load_dwordx2 v[96:97], v151, s[60:61]
	s_sub_u32 s60, s60, 0x1000
	s_subb_u32 s61, s61, 0
	global_load_dwordx2 v[98:99], v151, s[60:61]
	s_sub_u32 s60, s60, 0x1000
	s_subb_u32 s61, s61, 0
	global_load_dwordx2 v[100:101], v151, s[60:61]
	s_sub_u32 s60, s60, 0x1000
	s_subb_u32 s61, s61, 0
	global_load_dwordx2 v[102:103], v151, s[60:61]
	s_sub_u32 s60, s60, 0x1000
	s_subb_u32 s61, s61, 0
	global_load_dwordx2 v[104:105], v151, s[60:61]
	s_sub_u32 s60, s60, 0x1000
	s_subb_u32 s61, s61, 0
	global_load_dwordx2 v[106:107], v151, s[60:61]
	s_sub_u32 s60, s60, 0x1000
	s_subb_u32 s61, s61, 0
	global_load_dwordx2 v[108:109], v151, s[60:61]
	s_sub_u32 s60, s60, 0x1000
	s_subb_u32 s61, s61, 0
	global_load_dwordx2 v[110:111], v151, s[60:61]
	s_sub_u32 s60, s60, 0x1000
	s_subb_u32 s61, s61, 0
	global_load_dwordx2 v[112:113], v151, s[60:61]
	s_sub_u32 s60, s60, 0x1000
	s_subb_u32 s61, s61, 0
	global_load_dwordx2 v[114:115], v151, s[60:61]
	s_sub_u32 s60, s60, 0x1000
	s_subb_u32 s61, s61, 0
	global_load_dwordx2 v[116:117], v151, s[60:61]
	s_sub_u32 s60, s60, 0x1000
	s_subb_u32 s61, s61, 0
	global_load_dwordx2 v[118:119], v151, s[60:61]
	s_sub_u32 s60, s60, 0x1000
	s_subb_u32 s61, s61, 0
	global_load_dwordx2 v[120:121], v151, s[60:61]
	s_sub_u32 s60, s60, 0x1000
	s_subb_u32 s61, s61, 0
	global_load_dwordx2 v[122:123], v151, s[60:61]
	s_sub_u32 s60, s60, 0x1000
	s_subb_u32 s61, s61, 0
	global_load_dwordx2 v[124:125], v151, s[60:61]
	s_waitcnt vmcnt(34)
	v_fma_f32 v148, v0, v148, v1
	v_fma_f32 v148, v2, v148, v3
	v_mov_b32_e32 v253, 1.0
	v_mov_b32_e32 v254, 0
	s_waitcnt vmcnt(18)
	v_cmp_lt_i32_e32 vcc, 0, v150
	s_nop 1
	v_cndmask_b32_e32 v4, 1.0, v4, vcc
	v_cndmask_b32_e32 v5, 0, v5, vcc
	v_fma_f32 v254, v4, v254, v5
	v_mul_f32_e32 v253, v253, v4
	v_cmp_lt_i32_e32 vcc, 1, v150
	s_nop 1
	v_cndmask_b32_e32 v6, 1.0, v6, vcc
	v_cndmask_b32_e32 v7, 0, v7, vcc
	v_fma_f32 v254, v6, v254, v7
	v_mul_f32_e32 v253, v253, v6
	v_cmp_lt_i32_e32 vcc, 2, v150
	s_nop 1
	v_cndmask_b32_e32 v8, 1.0, v8, vcc
	v_cndmask_b32_e32 v9, 0, v9, vcc
	v_fma_f32 v254, v8, v254, v9
	v_mul_f32_e32 v253, v253, v8
	v_cmp_lt_i32_e32 vcc, 3, v150
	s_nop 1
	v_cndmask_b32_e32 v10, 1.0, v10, vcc
	v_cndmask_b32_e32 v11, 0, v11, vcc
	v_fma_f32 v254, v10, v254, v11
	v_mul_f32_e32 v253, v253, v10
	v_cmp_lt_i32_e32 vcc, 4, v150
	s_nop 1
	v_cndmask_b32_e32 v12, 1.0, v12, vcc
	v_cndmask_b32_e32 v13, 0, v13, vcc
	v_fma_f32 v254, v12, v254, v13
	v_mul_f32_e32 v253, v253, v12
	v_cmp_lt_i32_e32 vcc, 5, v150
	s_nop 1
	v_cndmask_b32_e32 v14, 1.0, v14, vcc
	v_cndmask_b32_e32 v15, 0, v15, vcc
	v_fma_f32 v254, v14, v254, v15
	v_mul_f32_e32 v253, v253, v14
	v_cmp_lt_i32_e32 vcc, 6, v150
	s_nop 1
	v_cndmask_b32_e32 v16, 1.0, v16, vcc
	v_cndmask_b32_e32 v17, 0, v17, vcc
	v_fma_f32 v254, v16, v254, v17
	v_mul_f32_e32 v253, v253, v16
	v_cmp_lt_i32_e32 vcc, 7, v150
	s_nop 1
	v_cndmask_b32_e32 v18, 1.0, v18, vcc
	v_cndmask_b32_e32 v19, 0, v19, vcc
	v_fma_f32 v254, v18, v254, v19
	v_mul_f32_e32 v253, v253, v18
	v_cmp_lt_i32_e32 vcc, 8, v150
	s_nop 1
	v_cndmask_b32_e32 v20, 1.0, v20, vcc
	v_cndmask_b32_e32 v21, 0, v21, vcc
	v_fma_f32 v254, v20, v254, v21
	v_mul_f32_e32 v253, v253, v20
	v_cmp_lt_i32_e32 vcc, 9, v150
	s_nop 1
	v_cndmask_b32_e32 v22, 1.0, v22, vcc
	v_cndmask_b32_e32 v23, 0, v23, vcc
	v_fma_f32 v254, v22, v254, v23
	v_mul_f32_e32 v253, v253, v22
	v_cmp_lt_i32_e32 vcc, 10, v150
	s_nop 1
	v_cndmask_b32_e32 v24, 1.0, v24, vcc
	v_cndmask_b32_e32 v25, 0, v25, vcc
	v_fma_f32 v254, v24, v254, v25
	v_mul_f32_e32 v253, v253, v24
	v_cmp_lt_i32_e32 vcc, 11, v150
	s_nop 1
	v_cndmask_b32_e32 v26, 1.0, v26, vcc
	v_cndmask_b32_e32 v27, 0, v27, vcc
	v_fma_f32 v254, v26, v254, v27
	v_mul_f32_e32 v253, v253, v26
	v_cmp_lt_i32_e32 vcc, 12, v150
	s_nop 1
	v_cndmask_b32_e32 v28, 1.0, v28, vcc
	v_cndmask_b32_e32 v29, 0, v29, vcc
	v_fma_f32 v254, v28, v254, v29
	v_mul_f32_e32 v253, v253, v28
	v_cmp_lt_i32_e32 vcc, 13, v150
	s_nop 1
	v_cndmask_b32_e32 v30, 1.0, v30, vcc
	v_cndmask_b32_e32 v31, 0, v31, vcc
	v_fma_f32 v254, v30, v254, v31
	v_mul_f32_e32 v253, v253, v30
	v_cmp_lt_i32_e32 vcc, 14, v150
	s_nop 1
	v_cndmask_b32_e32 v32, 1.0, v32, vcc
	v_cndmask_b32_e32 v33, 0, v33, vcc
	v_fma_f32 v254, v32, v254, v33
	v_mul_f32_e32 v253, v253, v32
	v_cmp_lt_i32_e32 vcc, 15, v150
	s_nop 1
	v_cndmask_b32_e32 v34, 1.0, v34, vcc
	v_cndmask_b32_e32 v35, 0, v35, vcc
	v_fma_f32 v254, v34, v254, v35
	v_mul_f32_e32 v253, v253, v34
	v_mov_b32_e32 v138, v253
	v_mov_b32_e32 v139, v253
	s_nop 1
	v_permlane16_swap_b32_e32 v138, v139
	v_mov_b32_e32 v140, v138
	v_mov_b32_e32 v141, v139
	s_nop 1
	v_permlane32_swap_b32_e32 v138, v140
	v_permlane32_swap_b32_e32 v139, v141
	v_mov_b32_e32 v198, v254
	v_mov_b32_e32 v199, v254
	s_nop 1
	v_permlane16_swap_b32_e32 v198, v199
	v_mov_b32_e32 v200, v198
	v_mov_b32_e32 v201, v199
	s_nop 1
	v_permlane32_swap_b32_e32 v198, v200
	v_permlane32_swap_b32_e32 v199, v201
	v_fma_f32 v148, v138, v148, v198
	v_fma_f32 v148, v139, v148, v199
	v_fma_f32 v148, v140, v148, v200
	v_fma_f32 v148, v141, v148, v201
	s_waitcnt vmcnt(16)
; __device__ __forceinline__ void lru_tile(const Params& P, int chunk, int head, int pass, char* smem_raw) {
;     ...
;       } else {
;         float2 s = S[(long)(256 + 2 * b + 1) * 512]; h = s.x * h + s.y;
;         s = S[(long)(256 + 2 * b) * 512]; h = s.x * h + s.y;
;         int i = 63;
;         for (; i - 8 >= j; i -= 8) {
;           float2 sv[8];
; #pragma unroll
;           for (int u = 0; u < 8; ++u) sv[u] = S[(long)(b * 64 + i - u) * 512];
; #pragma unroll
;           for (int u = 0; u < 8; ++u) h = sv[u].x * h + sv[u].y;
;         }
;         for (; i > j; --i) { s = S[(long)(b * 64 + i) * 512]; h = s.x * h + s.y; }
;       }
;     } else {
;       const int b = (chunk - 256) >> 1, j = (chunk - 256) & 1;
;       if (d == 0) { if (j == 1) { const float2 s = S[(long)(256 + 2 * b) * 512]; h = s.y; } }
;       else        { if (j == 0) { const float2 s = S[(long)(256 + 2 * b + 1) * 512]; h = s.y; } }
;     }
;     sm_init[d * 64 + ch] = h;
	v_fma_f32 v149, v90, v149, v91
	v_fma_f32 v149, v92, v149, v93
	v_mov_b32_e32 v253, 1.0
	v_mov_b32_e32 v254, 0
	s_waitcnt vmcnt(0)
	v_cmp_lt_i32_e32 vcc, 0, v202
	s_nop 1
	v_cndmask_b32_e32 v94, 1.0, v94, vcc
	v_cndmask_b32_e32 v95, 0, v95, vcc
	v_fma_f32 v254, v94, v254, v95
	v_mul_f32_e32 v253, v253, v94
	v_cmp_lt_i32_e32 vcc, 1, v202
	s_nop 1
	v_cndmask_b32_e32 v96, 1.0, v96, vcc
	v_cndmask_b32_e32 v97, 0, v97, vcc
	v_fma_f32 v254, v96, v254, v97
	v_mul_f32_e32 v253, v253, v96
	v_cmp_lt_i32_e32 vcc, 2, v202
	s_nop 1
	v_cndmask_b32_e32 v98, 1.0, v98, vcc
	v_cndmask_b32_e32 v99, 0, v99, vcc
	v_fma_f32 v254, v98, v254, v99
	v_mul_f32_e32 v253, v253, v98
	v_cmp_lt_i32_e32 vcc, 3, v202
	s_nop 1
	v_cndmask_b32_e32 v100, 1.0, v100, vcc
	v_cndmask_b32_e32 v101, 0, v101, vcc
	v_fma_f32 v254, v100, v254, v101
	v_mul_f32_e32 v253, v253, v100
	v_cmp_lt_i32_e32 vcc, 4, v202
	s_nop 1
	v_cndmask_b32_e32 v102, 1.0, v102, vcc
	v_cndmask_b32_e32 v103, 0, v103, vcc
	v_fma_f32 v254, v102, v254, v103
	v_mul_f32_e32 v253, v253, v102
	v_cmp_lt_i32_e32 vcc, 5, v202
	s_nop 1
	v_cndmask_b32_e32 v104, 1.0, v104, vcc
	v_cndmask_b32_e32 v105, 0, v105, vcc
	v_fma_f32 v254, v104, v254, v105
	v_mul_f32_e32 v253, v253, v104
	v_cmp_lt_i32_e32 vcc, 6, v202
	s_nop 1
	v_cndmask_b32_e32 v106, 1.0, v106, vcc
	v_cndmask_b32_e32 v107, 0, v107, vcc
	v_fma_f32 v254, v106, v254, v107
	v_mul_f32_e32 v253, v253, v106
	v_cmp_lt_i32_e32 vcc, 7, v202
	s_nop 1
	v_cndmask_b32_e32 v108, 1.0, v108, vcc
	v_cndmask_b32_e32 v109, 0, v109, vcc
	v_fma_f32 v254, v108, v254, v109
	v_mul_f32_e32 v253, v253, v108
	v_cmp_lt_i32_e32 vcc, 8, v202
	s_nop 1
	v_cndmask_b32_e32 v110, 1.0, v110, vcc
	v_cndmask_b32_e32 v111, 0, v111, vcc
	v_fma_f32 v254, v110, v254, v111
	v_mul_f32_e32 v253, v253, v110
	v_cmp_lt_i32_e32 vcc, 9, v202
	s_nop 1
	v_cndmask_b32_e32 v112, 1.0, v112, vcc
	v_cndmask_b32_e32 v113, 0, v113, vcc
	v_fma_f32 v254, v112, v254, v113
	v_mul_f32_e32 v253, v253, v112
	v_cmp_lt_i32_e32 vcc, 10, v202
	s_nop 1
	v_cndmask_b32_e32 v114, 1.0, v114, vcc
	v_cndmask_b32_e32 v115, 0, v115, vcc
	v_fma_f32 v254, v114, v254, v115
	v_mul_f32_e32 v253, v253, v114
	v_cmp_lt_i32_e32 vcc, 11, v202
	s_nop 1
	v_cndmask_b32_e32 v116, 1.0, v116, vcc
	v_cndmask_b32_e32 v117, 0, v117, vcc
	v_fma_f32 v254, v116, v254, v117
	v_mul_f32_e32 v253, v253, v116
	v_cmp_lt_i32_e32 vcc, 12, v202
	s_nop 1
	v_cndmask_b32_e32 v118, 1.0, v118, vcc
	v_cndmask_b32_e32 v119, 0, v119, vcc
	v_fma_f32 v254, v118, v254, v119
	v_mul_f32_e32 v253, v253, v118
	v_cmp_lt_i32_e32 vcc, 13, v202
	s_nop 1
	v_cndmask_b32_e32 v120, 1.0, v120, vcc
	v_cndmask_b32_e32 v121, 0, v121, vcc
	v_fma_f32 v254, v120, v254, v121
	v_mul_f32_e32 v253, v253, v120
	v_cmp_lt_i32_e32 vcc, 14, v202
	s_nop 1
	v_cndmask_b32_e32 v122, 1.0, v122, vcc
	v_cndmask_b32_e32 v123, 0, v123, vcc
	v_fma_f32 v254, v122, v254, v123
	v_mul_f32_e32 v253, v253, v122
	v_cmp_lt_i32_e32 vcc, 15, v202
	s_nop 1
	v_cndmask_b32_e32 v124, 1.0, v124, vcc
	v_cndmask_b32_e32 v125, 0, v125, vcc
	v_fma_f32 v254, v124, v254, v125
	v_mul_f32_e32 v253, v253, v124
	v_mov_b32_e32 v138, v253
	v_mov_b32_e32 v139, v253
	s_nop 1
	v_permlane16_swap_b32_e32 v138, v139
	v_mov_b32_e32 v140, v138
	v_mov_b32_e32 v141, v139
	s_nop 1
	v_permlane32_swap_b32_e32 v138, v140
	v_permlane32_swap_b32_e32 v139, v141
	v_mov_b32_e32 v198, v254
	v_mov_b32_e32 v199, v254
	s_nop 1
	v_permlane16_swap_b32_e32 v198, v199
	v_mov_b32_e32 v200, v198
	v_mov_b32_e32 v201, v199
	s_nop 1
	v_permlane32_swap_b32_e32 v198, v200
	v_permlane32_swap_b32_e32 v199, v201
	v_fma_f32 v149, v138, v149, v198
	v_fma_f32 v149, v139, v149, v199
	v_fma_f32 v149, v140, v149, v200
	v_fma_f32 v149, v141, v149, v201
	s_branch .Lmy_lrub_lbdone
.Lmy_lrub_lbctx:
	s_lshl_b32 s0, s56, 3
	s_add_u32 s0, s0, 0x0
	s_add_u32 s4, s18, s0
	s_addc_u32 s5, s19, 0
	s_sub_u32 s0, s71, 256
	s_and_b32 s1, s0, 1
	s_cmp_eq_u32 s1, 1
	s_cbranch_scc0 .Lmy_lrub_lbc0
	s_and_b32 s0, s0, -2
	s_add_u32 s0, s0, 256
	s_lshl_b32 s0, s0, 12
	s_add_u32 s60, s4, s0
	s_addc_u32 s61, s5, 0
	global_load_dwordx2 v[0:1], v250, s[60:61]
	s_waitcnt vmcnt(0)
	v_mov_b32_e32 v148, v1
; __device__ __forceinline__ float bf2f(u16 h) { return __uint_as_float(((unsigned)h) << 16); }
; __device__ __forceinline__ void lru_tile(const Params& P, int chunk, int head, int pass, char* smem_raw) {
;     ...
;     const int r = row0 + q * 32;
;     float uv[35];
; #pragma unroll
;     for (int i = 0; i < 35; ++i) {
;       const int rr = r - 2 + i;
;       uv[i] = (rr >= seq_lo && rr < seq_hi) ? bf2f(zu[(long)rr * 1536]) : 0.f;
;     ...
;       const int b = (chunk - 256) >> 1, j = (chunk - 256) & 1;
;       if (d == 0) { if (j == 1) { const float2 s = S[(long)(256 + 2 * b) * 512]; h = s.y; } }
;       else        { if (j == 0) { const float2 s = S[(long)(256 + 2 * b + 1) * 512]; h = s.y; } }
;     }
;     sm_init[d * 64 + ch] = h;
.Lmy_lrub_lbc0:
	s_lshl_b32 s0, s56, 3
	s_add_u32 s0, s0, 0x108000
	s_add_u32 s4, s18, s0
	s_addc_u32 s5, s19, 0
	s_sub_u32 s0, s71, 256
	s_and_b32 s1, s0, 1
	s_cmp_eq_u32 s1, 0
	s_cbranch_scc0 .Lmy_lrub_lbc1
	s_and_b32 s0, s0, -2
	s_add_u32 s0, s0, 257
	s_lshl_b32 s0, s0, 12
	s_add_u32 s60, s4, s0
	s_addc_u32 s61, s5, 0
	global_load_dwordx2 v[0:1], v250, s[60:61]
	s_waitcnt vmcnt(0)
	v_mov_b32_e32 v149, v1
.Lmy_lrub_lbc1:
.Lmy_lrub_lbdone:
	s_add_u32 s58, s69, 1
	s_cmp_lt_u32 s58, s70
	s_cbranch_scc0 .Lmy_lrub_nopf
	s_lshl_b32 s58, s58, 9
	s_add_u32 s58, s58, s68
	s_lshr_b32 s59, s58, 3
	s_cmp_lt_u32 s59, 256
	s_cselect_b32 s60, 63, 1
	s_and_b32 s57, s59, s60
	s_cmp_eq_u32 s57, 0
	s_cselect_b64 s[0:1], s[84:85], 0
	s_cmp_eq_u32 s57, s60
	s_cselect_b64 s[4:5], s[86:87], 0
	v_mov_b32_e32 v255, 0x1800
	v_cndmask_b32_e64 v150, 0, v255, s[0:1]
	v_lshlrev_b32_e32 v136, 1, v150
	v_add_u32_e32 v136, v134, v136
	v_add_u32_e32 v150, v134, v150
	v_cndmask_b32_e64 v151, 0, v255, s[4:5]
	v_sub_u32_e32 v151, v134, v151
	s_lshl_b32 s61, s59, 7
	s_mul_i32 s0, s61, 0xc00
	s_lshl_b32 s1, s56, 1
	s_add_u32 s0, s0, s1
	s_add_u32 s4, s10, s0
	s_addc_u32 s5, s11, 0
	s_sub_u32 s4, s4, 0x1800
	s_subb_u32 s5, s5, 0
	global_load_ushort v32, v136, s[4:5]
	s_add_u32 s4, s4, 0xc00
	s_addc_u32 s5, s5, 0
	global_load_ushort v33, v150, s[4:5]
	s_add_u32 s4, s4, 0xc00
	s_addc_u32 s5, s5, 0
	global_load_ushort v34, v134, s[4:5]
	s_add_u32 s4, s4, 0xc00
	s_addc_u32 s5, s5, 0
	global_load_ushort v35, v134, s[4:5]
	s_add_u32 s4, s4, 0xc00
	s_addc_u32 s5, s5, 0
	global_load_ushort v36, v134, s[4:5]
	s_add_u32 s4, s4, 0xc00
	s_addc_u32 s5, s5, 0
	global_load_ushort v37, v134, s[4:5]
	s_add_u32 s4, s4, 0xc00
	s_addc_u32 s5, s5, 0
	global_load_ushort v38, v134, s[4:5]
	s_add_u32 s4, s4, 0xc00
	s_addc_u32 s5, s5, 0
	global_load_ushort v39, v134, s[4:5]
	s_add_u32 s4, s4, 0xc00
	s_addc_u32 s5, s5, 0
	global_load_ushort v40, v134, s[4:5]
	s_add_u32 s4, s4, 0xc00
	s_addc_u32 s5, s5, 0
	global_load_ushort v41, v134, s[4:5]
	s_add_u32 s4, s4, 0xc00
	s_addc_u32 s5, s5, 0
	global_load_ushort v42, v134, s[4:5]
	s_add_u32 s4, s4, 0xc00
	s_addc_u32 s5, s5, 0
	global_load_ushort v43, v134, s[4:5]
	s_add_u32 s4, s4, 0xc00
	s_addc_u32 s5, s5, 0
	global_load_ushort v44, v134, s[4:5]
	s_add_u32 s4, s4, 0xc00
	s_addc_u32 s5, s5, 0
	global_load_ushort v45, v134, s[4:5]
	s_add_u32 s4, s4, 0xc00
	s_addc_u32 s5, s5, 0
	global_load_ushort v46, v134, s[4:5]
	s_add_u32 s4, s4, 0xc00
	s_addc_u32 s5, s5, 0
	global_load_ushort v47, v134, s[4:5]
	s_add_u32 s4, s4, 0xc00
	s_addc_u32 s5, s5, 0
	global_load_ushort v48, v134, s[4:5]
	s_add_u32 s4, s4, 0xc00
	s_addc_u32 s5, s5, 0
	global_load_ushort v49, v134, s[4:5]
	s_add_u32 s4, s4, 0xc00
	s_addc_u32 s5, s5, 0
	global_load_ushort v50, v134, s[4:5]
	s_add_u32 s4, s4, 0xc00
	s_addc_u32 s5, s5, 0
	global_load_ushort v51, v134, s[4:5]
	s_add_u32 s4, s4, 0xc00
	s_addc_u32 s5, s5, 0
	global_load_ushort v52, v134, s[4:5]
	s_add_u32 s4, s4, 0xc00
	s_addc_u32 s5, s5, 0
	global_load_ushort v53, v134, s[4:5]
	s_add_u32 s4, s4, 0xc00
	s_addc_u32 s5, s5, 0
	global_load_ushort v54, v134, s[4:5]
	s_add_u32 s4, s4, 0xc00
	s_addc_u32 s5, s5, 0
	global_load_ushort v55, v134, s[4:5]
	s_add_u32 s4, s4, 0xc00
	s_addc_u32 s5, s5, 0
	global_load_ushort v56, v134, s[4:5]
	s_add_u32 s4, s4, 0xc00
	s_addc_u32 s5, s5, 0
	global_load_ushort v57, v134, s[4:5]
	s_add_u32 s4, s4, 0xc00
	s_addc_u32 s5, s5, 0
	global_load_ushort v58, v134, s[4:5]
	s_add_u32 s4, s4, 0xc00
	s_addc_u32 s5, s5, 0
	global_load_ushort v59, v134, s[4:5]
	s_add_u32 s4, s4, 0xc00
	s_addc_u32 s5, s5, 0
	global_load_ushort v60, v134, s[4:5]
	s_add_u32 s4, s4, 0xc00
	s_addc_u32 s5, s5, 0
	global_load_ushort v61, v134, s[4:5]
	s_add_u32 s4, s4, 0xc00
	s_addc_u32 s5, s5, 0
	global_load_ushort v62, v134, s[4:5]
	s_add_u32 s4, s4, 0xc00
	s_addc_u32 s5, s5, 0
	global_load_ushort v63, v134, s[4:5]
	s_add_u32 s4, s4, 0xc00
	s_addc_u32 s5, s5, 0
	global_load_ushort v64, v134, s[4:5]
	s_add_u32 s4, s4, 0xc00
	s_addc_u32 s5, s5, 0
	global_load_ushort v66, v134, s[4:5]
	s_add_u32 s4, s4, 0xc00
	s_addc_u32 s5, s5, 0
	global_load_ushort v69, v151, s[4:5]
